# FNet A/C jobs (K=128): redundant clamped tile re-load, its LDS staging pass and barrier removed
# speedup vs baseline: 1.0067x; 1.0032x over previous
.LBB0_252:
	s_add_i32 s0, s6, 0xfffffe20
	s_lshr_b32 s4, s0, 1
	s_bfe_u32 s2, s0, 0x70001
	s_lshl_b32 s0, s0, 5
	s_and_b32 s0, s0, 0x7fffe000
	s_or_b32 s78, s0, s2
	s_waitcnt vmcnt(7)
	v_mov_b32_e32 v36, v208
	s_lshl_b64 s[0:1], s[78:79], 10
	v_readlane_b32 s8, v254, 1
	v_readlane_b32 s9, v254, 2
	v_lshlrev_b32_e32 v1, 7, v36
	s_add_u32 s0, s8, s0
	v_and_b32_e32 v39, 0x2f80, v1
	v_ashrrev_i32_e32 v1, 1, v36
	s_addc_u32 s1, s9, s1
	s_lshl_b32 s2, s2, 15
	v_readlane_b32 s8, v253, 36
	v_and_b32_e32 v37, 31, v36
	v_and_b32_e32 v38, 0xffffffc0, v1
	v_ashrrev_i32_e32 v72, 3, v36
	v_readlane_b32 s9, v253, 37
	s_add_u32 s2, s8, s2
	v_lshrrev_b32_e32 v0, 5, v36
	v_and_b32_e32 v5, 7, v36
	v_or_b32_e32 v1, v38, v37
	v_ashrrev_i32_e32 v73, 31, v72
	s_addc_u32 s3, s9, 0
	v_lshl_add_u32 v100, v1, 7, v214
	v_bitop3_b32 v6, v0, v5, 1 bitop3:0x6c
	v_lshlrev_b64 v[0:1], 8, v[72:73]
	v_lshlrev_b32_e32 v3, 4, v36
	v_lshl_add_u64 v[0:1], s[2:3], 0, v[0:1]
	v_and_b32_e32 v192, 0x70, v3
	v_lshl_add_u64 v[32:33], v[0:1], 0, v[192:193]
	global_load_dwordx4 v[40:43], v[32:33], off
	s_mov_b32 s5, s79
	s_lshl_b64 s[4:5], s[4:5], 16
	v_readlane_b32 s7, v254, 5
	s_add_u32 s4, s7, s4
	v_readlane_b32 s7, v254, 6
	v_ashrrev_i32_e32 v74, 4, v36
	s_addc_u32 s5, s7, s5
	s_lshl_b32 s7, s6, 7
	v_ashrrev_i32_e32 v75, 31, v74
	s_and_b32 s7, s7, 0x80
	v_lshlrev_b32_e32 v2, 3, v36
	v_lshlrev_b64 v[0:1], 9, v[74:75]
	v_add_u32_e32 v7, 0x100, v36
	v_lshl_add_u64 v[0:1], s[4:5], 0, v[0:1]
	s_lshl_b32 s78, s7, 1
	v_and_b32_e32 v73, 0x78, v2
	v_ashrrev_i32_e32 v76, 3, v7
	v_lshl_add_u64 v[0:1], v[0:1], 0, s[78:79]
	v_lshlrev_b32_e32 v2, 1, v73
	v_mov_b32_e32 v3, v193
	v_ashrrev_i32_e32 v77, 31, v76
	v_lshl_add_u64 v[12:13], v[0:1], 0, v[2:3]
	v_lshlrev_b64 v[0:1], 8, v[76:77]
	v_bfe_u32 v4, v36, 5, 1
	v_lshl_add_u64 v[0:1], s[2:3], 0, v[0:1]
	v_lshl_add_u64 v[34:35], v[0:1], 0, v[192:193]
	v_bitop3_b32 v0, v4, v5, 2 bitop3:0x36
	v_lshlrev_b32_e32 v77, 4, v0
	v_bitop3_b32 v0, v4, v5, 4 bitop3:0x36
	v_ashrrev_i32_e32 v78, 4, v7
	v_lshlrev_b32_e32 v101, 4, v0
	v_bitop3_b32 v0, v4, v5, 6 bitop3:0x36
	v_ashrrev_i32_e32 v79, 31, v78
	v_lshlrev_b32_e32 v102, 4, v0
	v_lshlrev_b64 v[0:1], 9, v[78:79]
	v_add_u32_e32 v4, 0x200, v36
	v_lshl_add_u64 v[0:1], s[4:5], 0, v[0:1]
	v_ashrrev_i32_e32 v80, 3, v4
	v_lshl_add_u64 v[0:1], v[0:1], 0, s[78:79]
	v_ashrrev_i32_e32 v81, 31, v80
	v_lshl_add_u64 v[14:15], v[0:1], 0, v[2:3]
	v_lshlrev_b64 v[0:1], 8, v[80:81]
	v_ashrrev_i32_e32 v84, 4, v4
	v_lshl_add_u64 v[0:1], s[2:3], 0, v[0:1]
	v_ashrrev_i32_e32 v85, 31, v84
	v_lshl_add_u64 v[82:83], v[0:1], 0, v[192:193]
	v_lshlrev_b64 v[0:1], 9, v[84:85]
	v_add_u32_e32 v8, 0x300, v36
	v_lshl_add_u64 v[0:1], s[4:5], 0, v[0:1]
	v_ashrrev_i32_e32 v86, 3, v8
	v_lshl_add_u64 v[0:1], v[0:1], 0, s[78:79]
	v_ashrrev_i32_e32 v87, 31, v86
	v_lshl_add_u64 v[24:25], v[0:1], 0, v[2:3]
	v_lshlrev_b64 v[0:1], 8, v[86:87]
	v_ashrrev_i32_e32 v90, 4, v8
	v_lshl_add_u64 v[0:1], s[2:3], 0, v[0:1]
	v_ashrrev_i32_e32 v91, 31, v90
	v_lshl_add_u64 v[88:89], v[0:1], 0, v[192:193]
	v_lshlrev_b64 v[0:1], 9, v[90:91]
	v_lshl_add_u64 v[0:1], s[4:5], 0, v[0:1]
	v_lshl_add_u64 v[0:1], v[0:1], 0, s[78:79]
	v_lshl_add_u64 v[26:27], v[0:1], 0, v[2:3]
	v_xor_b32_e32 v0, v72, v36
	v_lshlrev_b32_e32 v0, 4, v0
	v_and_b32_e32 v0, 0x70, v0
	global_load_dwordx4 v[44:47], v[34:35], off
	global_load_dwordx4 v[48:51], v[12:13], off
	v_lshlrev_b32_e32 v75, 4, v6
	global_load_dwordx4 v[4:7], v[34:35], off offset:128
	global_load_dwordx4 v[52:55], v[14:15], off
	global_load_dwordx4 v[16:19], v[32:33], off offset:128
	global_load_dwordx4 v[56:59], v[82:83], off
	global_load_dwordx4 v[8:11], v[82:83], off offset:128
	v_lshl_or_b32 v134, v72, 7, v0
	v_bfe_u32 v182, v208, 6, 2
	v_lshlrev_b32_e32 v182, 4, v182
	v_xor_b32_e32 v134, v182, v134
	global_load_dwordx4 v[60:63], v[88:89], off
	global_load_dwordx4 v[64:67], v[24:25], off
	global_load_dwordx4 v[0:3], v[88:89], off offset:128
	global_load_dwordx4 v[68:71], v[26:27], off
	s_mov_b32 s2, 0x8000
	v_add_co_u32_e32 v92, vcc, s2, v12
	s_movk_i32 s3, 0x50
	s_nop 0
	v_addc_co_u32_e32 v93, vcc, 0, v13, vcc
	v_add_co_u32_e32 v94, vcc, s2, v14
	s_movk_i32 s4, 0x60
	s_nop 0
	v_addc_co_u32_e32 v95, vcc, 0, v15, vcc
	v_add_co_u32_e32 v96, vcc, s2, v24
	global_load_dwordx4 v[28:31], v[92:93], off
	global_load_dwordx4 v[20:23], v[94:95], off
	v_addc_co_u32_e32 v97, vcc, 0, v25, vcc
	v_add_co_u32_e32 v98, vcc, s2, v26
	s_movk_i32 s2, 0x70
	s_nop 0
	v_addc_co_u32_e32 v99, vcc, 0, v27, vcc
	global_load_dwordx4 v[24:27], v[96:97], off
	global_load_dwordx4 v[12:15], v[98:99], off
	s_waitcnt vmcnt(15)
	ds_write_b128 v134, v[40:43]
	v_lshlrev_b32_e32 v40, 1, v74
	v_lshlrev_b32_e32 v41, 7, v73
	v_and_b32_e32 v42, -16, v72
	v_and_b32_e32 v40, 14, v40
	v_add_u32_e32 v43, v41, v42
	v_or_b32_e32 v135, v43, v40
	v_xad_u32 v43, v42, 16, v41
	v_or_b32_e32 v136, v43, v40
	v_xad_u32 v43, v42, 32, v41
	v_or_b32_e32 v137, v43, v40
	v_xad_u32 v43, v42, 48, v41
	v_or_b32_e32 v138, v43, v40
	v_xad_u32 v43, v42, 64, v41
	v_or_b32_e32 v139, v43, v40
	v_xad_u32 v43, v42, s3, v41
	v_or_b32_e32 v140, v43, v40
	v_xad_u32 v43, v42, s4, v41
	v_xad_u32 v42, v42, s2, v41
	v_or_b32_e32 v141, v43, v40
	v_or_b32_e32 v142, v42, v40
	v_xor_b32_e32 v40, v76, v36
	v_lshlrev_b32_e32 v40, 4, v40
	v_and_b32_e32 v40, 0x70, v40
	v_lshl_or_b32 v146, v76, 7, v40
	v_bfe_u32 v182, v208, 6, 2
	v_lshlrev_b32_e32 v182, 4, v182
	v_xor_b32_e32 v146, v182, v146
	v_lshlrev_b32_e32 v40, 1, v78
	v_and_b32_e32 v42, -16, v76
	v_and_b32_e32 v40, 14, v40
	v_add_u32_e32 v43, v41, v42
	v_or_b32_e32 v147, v43, v40
	v_xad_u32 v43, v42, 16, v41
	v_or_b32_e32 v148, v43, v40
	v_xad_u32 v43, v42, 32, v41
	v_or_b32_e32 v149, v43, v40
	v_xad_u32 v43, v42, 48, v41
	v_or_b32_e32 v150, v43, v40
	v_xad_u32 v43, v42, 64, v41
	v_or_b32_e32 v151, v43, v40
	v_xad_u32 v43, v42, s3, v41
	v_or_b32_e32 v152, v43, v40
	v_xad_u32 v43, v42, s4, v41
	v_xad_u32 v42, v42, s2, v41
	v_or_b32_e32 v153, v43, v40
	v_or_b32_e32 v154, v42, v40
	v_xor_b32_e32 v40, v80, v36
	v_lshlrev_b32_e32 v40, 4, v40
	v_and_b32_e32 v40, 0x70, v40
	v_lshl_or_b32 v156, v80, 7, v40
	v_bfe_u32 v182, v208, 6, 2
	v_lshlrev_b32_e32 v182, 4, v182
	v_xor_b32_e32 v156, v182, v156
	v_lshlrev_b32_e32 v40, 1, v84
	v_and_b32_e32 v42, -16, v80
	v_and_b32_e32 v40, 14, v40
	v_add_u32_e32 v43, v41, v42
	v_or_b32_e32 v157, v43, v40
	v_xad_u32 v43, v42, 16, v41
	v_or_b32_e32 v158, v43, v40
	v_xad_u32 v43, v42, 32, v41
	v_or_b32_e32 v159, v43, v40
	v_xad_u32 v43, v42, 48, v41
	v_or_b32_e32 v160, v43, v40
	v_xad_u32 v43, v42, 64, v41
	v_or_b32_e32 v161, v43, v40
	v_xad_u32 v43, v42, s3, v41
	v_or_b32_e32 v162, v43, v40
	v_xad_u32 v43, v42, s4, v41
	v_xad_u32 v42, v42, s2, v41
	v_or_b32_e32 v163, v43, v40
	v_or_b32_e32 v164, v42, v40
	v_xor_b32_e32 v40, v86, v36
	v_lshlrev_b32_e32 v40, 4, v40
	v_and_b32_e32 v40, 0x70, v40
	v_lshl_or_b32 v165, v86, 7, v40
	v_bfe_u32 v182, v208, 6, 2
	v_lshlrev_b32_e32 v182, 4, v182
	v_xor_b32_e32 v165, v182, v165
	v_lshlrev_b32_e32 v40, 1, v90
	v_and_b32_e32 v42, -16, v86
	v_and_b32_e32 v40, 14, v40
	v_add_u32_e32 v43, v41, v42
	v_or_b32_e32 v166, v43, v40
	v_xad_u32 v43, v42, 16, v41
	v_or_b32_e32 v167, v43, v40
	v_xad_u32 v43, v42, 32, v41
	v_or_b32_e32 v168, v43, v40
	v_xad_u32 v43, v42, 48, v41
	v_or_b32_e32 v169, v43, v40
	v_xad_u32 v43, v42, 64, v41
	v_or_b32_e32 v170, v43, v40
	v_xad_u32 v43, v42, s3, v41
	v_or_b32_e32 v171, v43, v40
	v_xad_u32 v43, v42, s4, v41
	v_xad_u32 v41, v42, s2, v41
	v_or_b32_e32 v172, v43, v40
	v_or_b32_e32 v173, v41, v40
	v_and_b32_e32 v175, 7, v208
	v_lshlrev_b32_e32 v175, 4, v175
	v_bfe_u32 v176, v208, 3, 2
	v_lshlrev_b32_e32 v176, 4, v176
	v_xor_b32_e32 v135, v175, v135
	v_xor_b32_e32 v136, v175, v136
	v_xor_b32_e32 v137, v175, v137
	v_xor_b32_e32 v138, v175, v138
	v_xor_b32_e32 v139, v175, v139
	v_xor_b32_e32 v140, v175, v140
	v_xor_b32_e32 v141, v175, v141
	v_xor_b32_e32 v142, v175, v142
	v_xor_b32_e32 v147, v175, v147
	v_xor_b32_e32 v148, v175, v148
	v_xor_b32_e32 v149, v175, v149
	v_xor_b32_e32 v150, v175, v150
	v_xor_b32_e32 v151, v175, v151
	v_xor_b32_e32 v152, v175, v152
	v_xor_b32_e32 v153, v175, v153
	v_xor_b32_e32 v154, v175, v154
	v_xor_b32_e32 v157, v175, v157
	v_xor_b32_e32 v158, v175, v158
	v_xor_b32_e32 v159, v175, v159
	v_xor_b32_e32 v160, v175, v160
	v_xor_b32_e32 v161, v175, v161
	v_xor_b32_e32 v162, v175, v162
	v_xor_b32_e32 v163, v175, v163
	v_xor_b32_e32 v164, v175, v164
	v_xor_b32_e32 v166, v175, v166
	v_xor_b32_e32 v167, v175, v167
	v_xor_b32_e32 v168, v175, v168
	v_xor_b32_e32 v169, v175, v169
	v_xor_b32_e32 v170, v175, v170
	v_xor_b32_e32 v171, v175, v171
	v_xor_b32_e32 v172, v175, v172
	v_xor_b32_e32 v173, v175, v173
	s_waitcnt vmcnt(13)
	ds_write_b16 v135, v48 offset:16384
	ds_write_b16_d16_hi v136, v48 offset:16512
	ds_write_b16 v137, v49 offset:16640
	ds_write_b16_d16_hi v138, v49 offset:16768
	ds_write_b16 v139, v50 offset:16896
	ds_write_b16_d16_hi v140, v50 offset:17024
	ds_write_b16 v141, v51 offset:17152
	ds_write_b16_d16_hi v142, v51 offset:17280
	ds_write_b128 v146, v[44:47]
	s_waitcnt vmcnt(11)
	ds_write_b16 v147, v52 offset:16384
	ds_write_b16_d16_hi v148, v52 offset:16512
	ds_write_b16 v149, v53 offset:16640
	ds_write_b16_d16_hi v150, v53 offset:16768
	ds_write_b16 v151, v54 offset:16896
	ds_write_b16_d16_hi v152, v54 offset:17024
	ds_write_b16 v153, v55 offset:17152
	ds_write_b16_d16_hi v154, v55 offset:17280
	s_waitcnt vmcnt(9)
	ds_write_b128 v156, v[56:59]
	s_waitcnt vmcnt(6)
	ds_write_b16 v157, v64 offset:16384
	ds_write_b16_d16_hi v158, v64 offset:16512
	ds_write_b16 v159, v65 offset:16640
	ds_write_b16_d16_hi v160, v65 offset:16768
	ds_write_b16 v161, v66 offset:16896
	ds_write_b16_d16_hi v162, v66 offset:17024
	ds_write_b16 v163, v67 offset:17152
	ds_write_b16_d16_hi v164, v67 offset:17280
	ds_write_b128 v165, v[60:63]
	s_waitcnt vmcnt(4)
	ds_write_b16 v166, v68 offset:16384
	ds_write_b16_d16_hi v167, v68 offset:16512
	ds_write_b16 v168, v69 offset:16640
	ds_write_b16_d16_hi v169, v69 offset:16768
	ds_write_b16 v170, v70 offset:16896
	ds_write_b16_d16_hi v171, v70 offset:17024
	ds_write_b16 v172, v71 offset:17152
	ds_write_b16_d16_hi v173, v71 offset:17280
	s_waitcnt lgkmcnt(0)
	s_barrier

	s_nop 0

	s_nop 0


	v_or_b32_e32 v132, v100, v75
	v_xor_b32_e32 v132, v176, v132
	v_xor_b32_e32 v177, 64, v132
	v_or_b32_e32 v143, v75, v39
	v_bfe_u32 v182, v208, 3, 2
	v_lshlrev_b32_e32 v182, 4, v182
	v_xor_b32_e32 v143, v182, v143
	v_or_b32_e32 v144, v101, v39
	v_bfe_u32 v182, v208, 3, 2
	v_lshlrev_b32_e32 v182, 4, v182
	v_xor_b32_e32 v144, v182, v144
	v_or_b32_e32 v145, v100, v77
	v_xor_b32_e32 v145, v176, v145
	v_xor_b32_e32 v180, 64, v145
	v_or_b32_e32 v155, v102, v39
	v_bfe_u32 v182, v208, 3, 2
	v_lshlrev_b32_e32 v182, 4, v182
	v_xor_b32_e32 v155, v182, v155
	v_or_b32_e32 v39, v77, v39
	v_bfe_u32 v182, v208, 3, 2
	v_lshlrev_b32_e32 v182, 4, v182
	v_xor_b32_e32 v39, v182, v39
	ds_read_b128 v[68:71], v143 offset:0
	ds_read_b128 v[72:75], v143 offset:0x1000
	ds_read_b128 v[76:79], v132 offset:0
	ds_read_b128 v[80:83], v177 offset:0x1000
	v_or_b32_e32 v133, v100, v101
	v_xor_b32_e32 v133, v176, v133
	v_xor_b32_e32 v178, 64, v133
	v_or_b32_e32 v174, v100, v102
	v_xor_b32_e32 v174, v176, v174
	v_xor_b32_e32 v181, 64, v174
	ds_read_b128 v[84:87], v39 offset:0
	ds_read_b128 v[88:91], v39 offset:0x1000
	ds_read_b128 v[92:95], v145 offset:0
	ds_read_b128 v[96:99], v180 offset:0x1000
	ds_read_b128 v[100:103], v144 offset:0
	ds_read_b128 v[104:107], v144 offset:0x1000
	ds_read_b128 v[108:111], v133 offset:0
	ds_read_b128 v[112:115], v178 offset:0x1000
	ds_read_b128 v[116:119], v155 offset:0
	ds_read_b128 v[120:123], v155 offset:0x1000
	ds_read_b128 v[124:127], v174 offset:0
	ds_read_b128 v[128:131], v181 offset:0x1000
	s_waitcnt lgkmcnt(12)
	s_nop 0
	v_mfma_f32_32x32x16_bf16 a[48:63], v[68:71], v[76:79], 0
	s_waitcnt lgkmcnt(8)
	s_waitcnt lgkmcnt(4)
	s_waitcnt lgkmcnt(0)
	ds_write_b128 v134, v[16:19] offset:32768
	s_waitcnt vmcnt(3)
	ds_write_b16 v135, v28 offset:49152
	ds_write_b16_d16_hi v136, v28 offset:49280
	ds_write_b16 v137, v29 offset:49408
	ds_write_b16_d16_hi v138, v29 offset:49536
	ds_write_b16 v139, v30 offset:49664
	ds_write_b16_d16_hi v140, v30 offset:49792
	ds_write_b16 v141, v31 offset:49920
	ds_write_b16_d16_hi v142, v31 offset:50048
	ds_write_b128 v146, v[4:7] offset:32768
	s_waitcnt vmcnt(2)
	ds_write_b16 v147, v20 offset:49152
	ds_write_b16_d16_hi v148, v20 offset:49280
	ds_write_b16 v149, v21 offset:49408
	ds_write_b16_d16_hi v150, v21 offset:49536
	ds_write_b16 v151, v22 offset:49664
	ds_write_b16_d16_hi v152, v22 offset:49792
	ds_write_b16 v153, v23 offset:49920
	ds_write_b16_d16_hi v154, v23 offset:50048
	ds_write_b128 v156, v[8:11] offset:32768
	s_waitcnt vmcnt(1)
	ds_write_b16 v157, v24 offset:49152
	ds_write_b16_d16_hi v158, v24 offset:49280
	ds_write_b16 v159, v25 offset:49408
	ds_write_b16_d16_hi v160, v25 offset:49536
	ds_write_b16 v161, v26 offset:49664
	ds_write_b16_d16_hi v162, v26 offset:49792
	ds_write_b16 v163, v27 offset:49920
	ds_write_b16_d16_hi v164, v27 offset:50048
	ds_write_b128 v165, v[0:3] offset:32768
	s_waitcnt vmcnt(0)
	ds_write_b16 v166, v12 offset:49152
	ds_write_b16_d16_hi v167, v12 offset:49280
	ds_write_b16 v168, v13 offset:49408
	ds_write_b16_d16_hi v169, v13 offset:49536
	ds_write_b16 v170, v14 offset:49664
	ds_write_b16_d16_hi v171, v14 offset:49792
	ds_write_b16 v172, v15 offset:49920
	ds_write_b16_d16_hi v173, v15 offset:50048
	s_waitcnt lgkmcnt(0)
	s_barrier
	v_mfma_f32_32x32x16_bf16 a[48:63], v[84:87], v[92:95], a[48:63]
	ds_read_b128 v[0:3], v143 offset:0x8000
	ds_read_b128 v[4:7], v143 offset:0x9000
	ds_read_b128 v[8:11], v132 offset:0x8000
	ds_read_b128 v[12:15], v177 offset:0x9000
	ds_read_b128 v[16:19], v39 offset:0x8000
	ds_read_b128 v[20:23], v39 offset:0x9000
	ds_read_b128 v[24:27], v145 offset:0x8000
	v_mfma_f32_32x32x16_bf16 a[48:63], v[100:103], v[108:111], a[48:63]
	ds_read_b128 v[28:31], v180 offset:0x9000
	v_mfma_f32_32x32x16_bf16 a[32:47], v[68:71], v[80:83], 0
	ds_read_b128 v[68:71], v144 offset:0x8000
	v_mfma_f32_32x32x16_bf16 a[16:31], v[72:75], v[76:79], 0
	v_mfma_f32_32x32x16_bf16 a[0:15], v[72:75], v[80:83], 0
	ds_read_b128 v[72:75], v144 offset:0x9000
	ds_read_b128 v[76:79], v133 offset:0x8000
	ds_read_b128 v[80:83], v178 offset:0x9000
	v_mfma_f32_32x32x16_bf16 a[48:63], v[116:119], v[124:127], a[48:63]
	v_mfma_f32_32x32x16_bf16 a[32:47], v[84:87], v[96:99], a[32:47]
	ds_read_b128 v[84:87], v155 offset:0x8000
	v_mfma_f32_32x32x16_bf16 a[16:31], v[88:91], v[92:95], a[16:31]
	v_mfma_f32_32x32x16_bf16 a[0:15], v[88:91], v[96:99], a[0:15]
	ds_read_b128 v[88:91], v155 offset:0x9000
	ds_read_b128 v[92:95], v174 offset:0x8000
	ds_read_b128 v[96:99], v181 offset:0x9000
	s_waitcnt lgkmcnt(12)
	s_waitcnt lgkmcnt(8)
	s_waitcnt lgkmcnt(4)
	s_nop 0
	v_mfma_f32_32x32x16_bf16 a[48:63], v[0:3], v[8:11], a[48:63]
	s_waitcnt lgkmcnt(0)


	v_mfma_f32_32x32x16_bf16 a[48:63], v[16:19], v[24:27], a[48:63]
	v_mfma_f32_32x32x16_bf16 a[32:47], v[100:103], v[112:115], a[32:47]
	v_mfma_f32_32x32x16_bf16 a[48:63], v[68:71], v[76:79], a[48:63]
	v_mfma_f32_32x32x16_bf16 a[16:31], v[104:107], v[108:111], a[16:31]
	v_mfma_f32_32x32x16_bf16 a[0:15], v[104:107], v[112:115], a[0:15]
	v_mfma_f32_32x32x16_bf16 a[32:47], v[116:119], v[128:131], a[32:47]
	v_mfma_f32_32x32x16_bf16 a[48:63], v[84:87], v[92:95], a[48:63]
	v_mfma_f32_32x32x16_bf16 a[16:31], v[120:123], v[124:127], a[16:31]
	v_mfma_f32_32x32x16_bf16 a[0:15], v[120:123], v[128:131], a[0:15]
	v_mfma_f32_32x32x16_bf16 a[32:47], v[0:3], v[12:15], a[32:47]
	v_and_b32_e32 v0, 64, v36
	v_lshrrev_b32_e32 v1, 3, v36
	v_and_or_b32 v2, v1, 4, v0
	v_or_b32_e32 v0, s7, v37
	v_add_u32_e32 v0, v0, v38
	s_nop 3
	v_accvgpr_read_b32 v3, a48
	v_ashrrev_i32_e32 v1, 31, v0
	v_lshlrev_b32_e32 v192, 16, v2
	v_mul_f32_e32 v2, 0x3ab504f3, v3
	v_lshl_add_u64 v[0:1], v[0:1], 1, s[0:1]
	v_bfe_u32 v3, v2, 16, 1
	v_mfma_f32_32x32x16_bf16 a[16:31], v[4:7], v[8:11], a[16:31]
	v_add3_u32 v2, v2, v3, s80
	s_mov_b32 s0, 0x20000
	v_accvgpr_read_b32 v8, a51
	v_accvgpr_read_b32 v10, a52
	v_mul_f32_e32 v10, 0x3ab504f3, v10
	v_mov_b32_e32 v9, v193
	v_accvgpr_read_b32 v11, a53
	v_mfma_f32_32x32x16_bf16 a[0:15], v[4:7], v[12:15], a[0:15]
	v_accvgpr_read_b32 v6, a49
	v_lshl_add_u64 v[4:5], v[0:1], 0, v[192:193]
	global_store_short_d16_hi v[4:5], v2, off
	v_mul_f32_e32 v2, 0x3ab504f3, v6
	v_bfe_u32 v3, v2, 16, 1
	v_accvgpr_read_b32 v7, a50
	v_add3_u32 v2, v2, v3, s80
	global_store_short_d16_hi v[4:5], v2, off offset:512
	v_mul_f32_e32 v2, 0x3ab504f3, v7
	v_bfe_u32 v3, v2, 16, 1
	v_add_co_u32_e32 v6, vcc, s0, v4
	v_add3_u32 v2, v2, v3, s80
	s_nop 0
	v_addc_co_u32_e32 v7, vcc, 0, v5, vcc
	global_store_short_d16_hi v[6:7], v2, off
	v_mul_f32_e32 v2, 0x3ab504f3, v8
	v_bfe_u32 v3, v2, 16, 1
	v_add3_u32 v2, v2, v3, s80
	v_or_b32_e32 v8, 0x80000, v192
	v_bfe_u32 v14, v10, 16, 1
	global_store_short_d16_hi v[6:7], v2, off offset:512
	v_lshl_add_u64 v[2:3], v[0:1], 0, v[8:9]
	v_add3_u32 v10, v10, v14, s80
	global_store_short_d16_hi v[2:3], v10, off
	v_mul_f32_e32 v10, 0x3ab504f3, v11
	v_bfe_u32 v11, v10, 16, 1
	v_accvgpr_read_b32 v12, a54
	v_add3_u32 v10, v10, v11, s80
	global_store_short_d16_hi v[2:3], v10, off offset:512
	v_mul_f32_e32 v10, 0x3ab504f3, v12
	v_bfe_u32 v11, v10, 16, 1
	v_add_co_u32_e32 v2, vcc, s0, v2
	v_accvgpr_read_b32 v13, a55
	v_add3_u32 v10, v10, v11, s80
	v_addc_co_u32_e32 v3, vcc, 0, v3, vcc
	global_store_short_d16_hi v[2:3], v10, off
	v_mul_f32_e32 v10, 0x3ab504f3, v13
	v_mfma_f32_32x32x16_bf16 a[32:47], v[16:19], v[28:31], a[32:47]
	v_bfe_u32 v11, v10, 16, 1
	v_accvgpr_read_b32 v12, a56
	v_add3_u32 v10, v10, v11, s80
	v_mul_f32_e32 v12, 0x3ab504f3, v12
	global_store_short_d16_hi v[2:3], v10, off offset:512
	v_or_b32_e32 v10, 0x100000, v192
	v_mov_b32_e32 v11, v193
	v_bfe_u32 v16, v12, 16, 1
	v_accvgpr_read_b32 v13, a57
	v_lshl_add_u64 v[2:3], v[0:1], 0, v[10:11]
	v_add3_u32 v12, v12, v16, s80
	global_store_short_d16_hi v[2:3], v12, off
	v_mul_f32_e32 v12, 0x3ab504f3, v13
	v_bfe_u32 v13, v12, 16, 1
	v_accvgpr_read_b32 v14, a58
	v_add3_u32 v12, v12, v13, s80
	global_store_short_d16_hi v[2:3], v12, off offset:512
	v_mul_f32_e32 v12, 0x3ab504f3, v14
	v_mfma_f32_32x32x16_bf16 a[32:47], v[68:71], v[80:83], a[32:47]
	v_bfe_u32 v13, v12, 16, 1
	v_add_co_u32_e32 v2, vcc, s0, v2
	v_accvgpr_read_b32 v15, a59
	v_add3_u32 v12, v12, v13, s80
	v_addc_co_u32_e32 v3, vcc, 0, v3, vcc
	global_store_short_d16_hi v[2:3], v12, off
	v_mul_f32_e32 v12, 0x3ab504f3, v15
	v_bfe_u32 v13, v12, 16, 1
	v_accvgpr_read_b32 v14, a60
	v_add3_u32 v12, v12, v13, s80
	v_mul_f32_e32 v14, 0x3ab504f3, v14
	global_store_short_d16_hi v[2:3], v12, off offset:512
	v_or_b32_e32 v12, 0x180000, v192
	v_mov_b32_e32 v13, v193
	v_bfe_u32 v18, v14, 16, 1
	v_accvgpr_read_b32 v15, a61
	v_lshl_add_u64 v[2:3], v[0:1], 0, v[12:13]
	v_add3_u32 v14, v14, v18, s80
	global_store_short_d16_hi v[2:3], v14, off
	v_mul_f32_e32 v14, 0x3ab504f3, v15
	v_mfma_f32_32x32x16_bf16 a[32:47], v[84:87], v[96:99], a[32:47]
	v_bfe_u32 v15, v14, 16, 1
	v_accvgpr_read_b32 v16, a62
	v_add3_u32 v14, v14, v15, s80
	global_store_short_d16_hi v[2:3], v14, off offset:512
	v_mul_f32_e32 v14, 0x3ab504f3, v16
	v_bfe_u32 v15, v14, 16, 1
	v_add_co_u32_e32 v2, vcc, s0, v2
	v_accvgpr_read_b32 v17, a63
	v_add3_u32 v14, v14, v15, s80
	v_addc_co_u32_e32 v3, vcc, 0, v3, vcc
	global_store_short_d16_hi v[2:3], v14, off
	v_mul_f32_e32 v14, 0x3ab504f3, v17
	v_bfe_u32 v15, v14, 16, 1
	v_add3_u32 v14, v14, v15, s80
	global_store_short_d16_hi v[2:3], v14, off offset:512
	v_accvgpr_read_b32 v14, a32
	v_mul_f32_e32 v14, 0x3ab504f3, v14
	v_bfe_u32 v18, v14, 16, 1
	v_accvgpr_read_b32 v15, a33
	v_add3_u32 v14, v14, v18, s80
	global_store_short_d16_hi v[4:5], v14, off offset:64
	v_mul_f32_e32 v14, 0x3ab504f3, v15
	v_bfe_u32 v15, v14, 16, 1
	v_accvgpr_read_b32 v16, a34
	v_add3_u32 v14, v14, v15, s80
	global_store_short_d16_hi v[4:5], v14, off offset:576
	v_mul_f32_e32 v4, 0x3ab504f3, v16
	v_bfe_u32 v5, v4, 16, 1
	v_accvgpr_read_b32 v17, a35
	v_add3_u32 v4, v4, v5, s80
	global_store_short_d16_hi v[6:7], v4, off offset:64
	v_mul_f32_e32 v4, 0x3ab504f3, v17
	v_bfe_u32 v5, v4, 16, 1
	v_add3_u32 v4, v4, v5, s80
	global_store_short_d16_hi v[6:7], v4, off offset:576
	v_accvgpr_read_b32 v6, a36
	v_lshl_add_u64 v[2:3], v[0:1], 0, 64
	v_mul_f32_e32 v6, 0x3ab504f3, v6
	v_lshl_add_u64 v[4:5], v[2:3], 0, v[8:9]
	v_bfe_u32 v8, v6, 16, 1
	v_accvgpr_read_b32 v7, a37
	v_add3_u32 v6, v6, v8, s80
	global_store_short_d16_hi v[4:5], v6, off
	v_mul_f32_e32 v6, 0x3ab504f3, v7
	v_bfe_u32 v7, v6, 16, 1
	v_accvgpr_read_b32 v14, a38
	v_add3_u32 v6, v6, v7, s80
	global_store_short_d16_hi v[4:5], v6, off offset:512
	v_mul_f32_e32 v6, 0x3ab504f3, v14
	v_bfe_u32 v7, v6, 16, 1
	v_add_co_u32_e32 v4, vcc, s0, v4
	v_accvgpr_read_b32 v15, a39
	v_add3_u32 v6, v6, v7, s80
	v_addc_co_u32_e32 v5, vcc, 0, v5, vcc
	global_store_short_d16_hi v[4:5], v6, off
	v_mul_f32_e32 v6, 0x3ab504f3, v15
	v_bfe_u32 v7, v6, 16, 1
	v_add3_u32 v6, v6, v7, s80
	v_mfma_f32_32x32x16_bf16 a[16:31], v[20:23], v[24:27], a[16:31]
	global_store_short_d16_hi v[4:5], v6, off offset:512
	v_accvgpr_read_b32 v6, a40
	v_mul_f32_e32 v6, 0x3ab504f3, v6
	v_lshl_add_u64 v[4:5], v[2:3], 0, v[10:11]
	v_bfe_u32 v10, v6, 16, 1
	v_accvgpr_read_b32 v7, a41
	v_add3_u32 v6, v6, v10, s80
	global_store_short_d16_hi v[4:5], v6, off
	v_mul_f32_e32 v6, 0x3ab504f3, v7
	v_bfe_u32 v7, v6, 16, 1
	v_accvgpr_read_b32 v8, a42
	v_add3_u32 v6, v6, v7, s80
	global_store_short_d16_hi v[4:5], v6, off offset:512
	v_mul_f32_e32 v6, 0x3ab504f3, v8
	v_mfma_f32_32x32x16_bf16 a[16:31], v[72:75], v[76:79], a[16:31]
	v_bfe_u32 v7, v6, 16, 1
	v_add_co_u32_e32 v4, vcc, s0, v4
	v_accvgpr_read_b32 v9, a43
	v_add3_u32 v6, v6, v7, s80
	v_addc_co_u32_e32 v5, vcc, 0, v5, vcc
	global_store_short_d16_hi v[4:5], v6, off
	v_mul_f32_e32 v6, 0x3ab504f3, v9
	v_bfe_u32 v7, v6, 16, 1
	v_add3_u32 v6, v6, v7, s80
	global_store_short_d16_hi v[4:5], v6, off offset:512
	v_accvgpr_read_b32 v6, a44
	v_mul_f32_e32 v6, 0x3ab504f3, v6
	v_bfe_u32 v10, v6, 16, 1
	v_mfma_f32_32x32x16_bf16 a[16:31], v[88:91], v[92:95], a[16:31]
	v_accvgpr_read_b32 v7, a45
	v_lshl_add_u64 v[4:5], v[2:3], 0, v[12:13]
	v_add3_u32 v6, v6, v10, s80
	global_store_short_d16_hi v[4:5], v6, off
	v_mul_f32_e32 v6, 0x3ab504f3, v7
	v_bfe_u32 v7, v6, 16, 1
	v_accvgpr_read_b32 v8, a46
	v_add3_u32 v6, v6, v7, s80
	global_store_short_d16_hi v[4:5], v6, off offset:512
	v_mul_f32_e32 v6, 0x3ab504f3, v8
	v_bfe_u32 v7, v6, 16, 1
	v_add_co_u32_e32 v4, vcc, s0, v4
	v_accvgpr_read_b32 v9, a47
	v_add3_u32 v6, v6, v7, s80
	v_addc_co_u32_e32 v5, vcc, 0, v5, vcc
	global_store_short_d16_hi v[4:5], v6, off
	v_mul_f32_e32 v6, 0x3ab504f3, v9
	v_bfe_u32 v7, v6, 16, 1
	v_accvgpr_read_b32 v8, a16
	v_add3_u32 v6, v6, v7, s80
	v_mul_f32_e32 v8, 0x3ab504f3, v8
	global_store_short_d16_hi v[4:5], v6, off offset:512
	v_or_b32_e32 v4, 0x200000, v192
	v_mov_b32_e32 v5, v193
	v_bfe_u32 v12, v8, 16, 1
	v_accvgpr_read_b32 v9, a17
	v_lshl_add_u64 v[6:7], v[0:1], 0, v[4:5]
	v_add3_u32 v8, v8, v12, s80
	global_store_short_d16_hi v[6:7], v8, off
	v_mul_f32_e32 v8, 0x3ab504f3, v9
	v_bfe_u32 v9, v8, 16, 1
	v_accvgpr_read_b32 v10, a18
	v_add3_u32 v8, v8, v9, s80
	global_store_short_d16_hi v[6:7], v8, off offset:512
	v_mul_f32_e32 v8, 0x3ab504f3, v10
	v_bfe_u32 v9, v8, 16, 1
	v_add_co_u32_e32 v6, vcc, s0, v6
	v_accvgpr_read_b32 v11, a19
	v_add3_u32 v8, v8, v9, s80
	v_addc_co_u32_e32 v7, vcc, 0, v7, vcc
	global_store_short_d16_hi v[6:7], v8, off
	v_mul_f32_e32 v8, 0x3ab504f3, v11
	v_bfe_u32 v9, v8, 16, 1
	v_accvgpr_read_b32 v10, a20
	v_add3_u32 v8, v8, v9, s80
	v_mul_f32_e32 v10, 0x3ab504f3, v10
	global_store_short_d16_hi v[6:7], v8, off offset:512
	v_or_b32_e32 v6, 0x280000, v192
	v_mov_b32_e32 v7, v193
	v_bfe_u32 v14, v10, 16, 1
	v_accvgpr_read_b32 v11, a21
	v_lshl_add_u64 v[8:9], v[0:1], 0, v[6:7]
	v_add3_u32 v10, v10, v14, s80
	global_store_short_d16_hi v[8:9], v10, off
	v_mul_f32_e32 v10, 0x3ab504f3, v11
	v_bfe_u32 v11, v10, 16, 1
	v_accvgpr_read_b32 v12, a22
	v_add3_u32 v10, v10, v11, s80
	global_store_short_d16_hi v[8:9], v10, off offset:512
	v_mul_f32_e32 v10, 0x3ab504f3, v12
	v_bfe_u32 v11, v10, 16, 1
	v_add_co_u32_e32 v8, vcc, s0, v8
	v_accvgpr_read_b32 v13, a23
	v_add3_u32 v10, v10, v11, s80
	v_addc_co_u32_e32 v9, vcc, 0, v9, vcc
	global_store_short_d16_hi v[8:9], v10, off
	v_mul_f32_e32 v10, 0x3ab504f3, v13
	v_bfe_u32 v11, v10, 16, 1
	v_accvgpr_read_b32 v12, a24
	v_add3_u32 v10, v10, v11, s80
	v_mul_f32_e32 v12, 0x3ab504f3, v12
	v_mfma_f32_32x32x16_bf16 a[0:15], v[20:23], v[28:31], a[0:15]
	global_store_short_d16_hi v[8:9], v10, off offset:512
	v_or_b32_e32 v8, 0x300000, v192
	v_mov_b32_e32 v9, v193
	v_bfe_u32 v16, v12, 16, 1
	v_accvgpr_read_b32 v13, a25
	v_lshl_add_u64 v[10:11], v[0:1], 0, v[8:9]
	v_add3_u32 v12, v12, v16, s80
	global_store_short_d16_hi v[10:11], v12, off
	v_mul_f32_e32 v12, 0x3ab504f3, v13
	v_bfe_u32 v13, v12, 16, 1
	v_accvgpr_read_b32 v14, a26
	v_add3_u32 v12, v12, v13, s80
	global_store_short_d16_hi v[10:11], v12, off offset:512
	v_mul_f32_e32 v12, 0x3ab504f3, v14
	v_bfe_u32 v13, v12, 16, 1
	v_add_co_u32_e32 v10, vcc, s0, v10
	v_accvgpr_read_b32 v15, a27
	v_add3_u32 v12, v12, v13, s80
	v_addc_co_u32_e32 v11, vcc, 0, v11, vcc
	v_mfma_f32_32x32x16_bf16 a[0:15], v[72:75], v[80:83], a[0:15]
	global_store_short_d16_hi v[10:11], v12, off
	v_mul_f32_e32 v12, 0x3ab504f3, v15
	v_bfe_u32 v13, v12, 16, 1
	v_add3_u32 v12, v12, v13, s80
	global_store_short_d16_hi v[10:11], v12, off offset:512
	v_accvgpr_read_b32 v10, a28
	v_mul_f32_e32 v10, 0x3ab504f3, v10
	v_or_b32_e32 v192, 0x380000, v192
	v_bfe_u32 v14, v10, 16, 1
	v_accvgpr_read_b32 v11, a29
	v_lshl_add_u64 v[0:1], v[0:1], 0, v[192:193]
	v_add3_u32 v10, v10, v14, s80
	global_store_short_d16_hi v[0:1], v10, off
	v_mul_f32_e32 v10, 0x3ab504f3, v11
	v_mfma_f32_32x32x16_bf16 a[0:15], v[88:91], v[96:99], a[0:15]
	v_bfe_u32 v11, v10, 16, 1
	v_accvgpr_read_b32 v12, a30
	v_add3_u32 v10, v10, v11, s80
	global_store_short_d16_hi v[0:1], v10, off offset:512
	v_mul_f32_e32 v10, 0x3ab504f3, v12
	v_bfe_u32 v11, v10, 16, 1
	v_add_co_u32_e32 v0, vcc, s0, v0
	v_accvgpr_read_b32 v13, a31
	v_add3_u32 v10, v10, v11, s80
	v_addc_co_u32_e32 v1, vcc, 0, v1, vcc
	global_store_short_d16_hi v[0:1], v10, off
	v_mul_f32_e32 v10, 0x3ab504f3, v13
	v_bfe_u32 v11, v10, 16, 1
	v_add3_u32 v10, v10, v11, s80
	global_store_short_d16_hi v[0:1], v10, off offset:512
	v_accvgpr_read_b32 v10, a0
	v_lshl_add_u64 v[0:1], v[2:3], 0, v[4:5]
	v_mul_f32_e32 v4, 0x3ab504f3, v10
	v_bfe_u32 v5, v4, 16, 1
	v_accvgpr_read_b32 v11, a1
	v_add3_u32 v4, v4, v5, s80
	global_store_short_d16_hi v[0:1], v4, off
	v_mul_f32_e32 v4, 0x3ab504f3, v11
	v_bfe_u32 v5, v4, 16, 1
	v_accvgpr_read_b32 v12, a2
	v_add3_u32 v4, v4, v5, s80
	global_store_short_d16_hi v[0:1], v4, off offset:512
	v_mul_f32_e32 v4, 0x3ab504f3, v12
	v_bfe_u32 v5, v4, 16, 1
	v_add_co_u32_e32 v0, vcc, s0, v0
	v_accvgpr_read_b32 v13, a3
	v_add3_u32 v4, v4, v5, s80
	v_addc_co_u32_e32 v1, vcc, 0, v1, vcc
	global_store_short_d16_hi v[0:1], v4, off
	v_mul_f32_e32 v4, 0x3ab504f3, v13
	v_bfe_u32 v5, v4, 16, 1
	v_add3_u32 v4, v4, v5, s80
	global_store_short_d16_hi v[0:1], v4, off offset:512
	v_accvgpr_read_b32 v4, a4
	v_mul_f32_e32 v4, 0x3ab504f3, v4
	v_lshl_add_u64 v[0:1], v[2:3], 0, v[6:7]
	v_bfe_u32 v6, v4, 16, 1
	v_accvgpr_read_b32 v5, a5
	v_add3_u32 v4, v4, v6, s80
	global_store_short_d16_hi v[0:1], v4, off
	v_mul_f32_e32 v4, 0x3ab504f3, v5
	v_bfe_u32 v5, v4, 16, 1
	v_accvgpr_read_b32 v10, a6
	v_add3_u32 v4, v4, v5, s80
	global_store_short_d16_hi v[0:1], v4, off offset:512
	v_mul_f32_e32 v4, 0x3ab504f3, v10
	v_bfe_u32 v5, v4, 16, 1
	v_add_co_u32_e32 v0, vcc, s0, v0
	v_accvgpr_read_b32 v11, a7
	v_add3_u32 v4, v4, v5, s80
	v_addc_co_u32_e32 v1, vcc, 0, v1, vcc
	global_store_short_d16_hi v[0:1], v4, off
	v_mul_f32_e32 v4, 0x3ab504f3, v11
	v_bfe_u32 v5, v4, 16, 1
	v_add3_u32 v4, v4, v5, s80
	global_store_short_d16_hi v[0:1], v4, off offset:512
	v_accvgpr_read_b32 v4, a8
	v_mul_f32_e32 v4, 0x3ab504f3, v4
	v_lshl_add_u64 v[0:1], v[2:3], 0, v[8:9]
	v_bfe_u32 v8, v4, 16, 1
	v_accvgpr_read_b32 v5, a9
	v_add3_u32 v4, v4, v8, s80
	global_store_short_d16_hi v[0:1], v4, off
	v_mul_f32_e32 v4, 0x3ab504f3, v5
	v_bfe_u32 v5, v4, 16, 1
	v_accvgpr_read_b32 v6, a10
	v_add3_u32 v4, v4, v5, s80
	global_store_short_d16_hi v[0:1], v4, off offset:512
	v_mul_f32_e32 v4, 0x3ab504f3, v6
	v_bfe_u32 v5, v4, 16, 1
	v_add_co_u32_e32 v0, vcc, s0, v0
	v_accvgpr_read_b32 v7, a11
	v_add3_u32 v4, v4, v5, s80
	v_addc_co_u32_e32 v1, vcc, 0, v1, vcc
	global_store_short_d16_hi v[0:1], v4, off
	v_mul_f32_e32 v4, 0x3ab504f3, v7
	v_bfe_u32 v5, v4, 16, 1
	v_add3_u32 v4, v4, v5, s80
	global_store_short_d16_hi v[0:1], v4, off offset:512
	v_accvgpr_read_b32 v4, a12
	v_lshl_add_u64 v[0:1], v[2:3], 0, v[192:193]
	v_mul_f32_e32 v2, 0x3ab504f3, v4
	v_bfe_u32 v3, v2, 16, 1
	v_accvgpr_read_b32 v5, a13
	v_add3_u32 v2, v2, v3, s80
	global_store_short_d16_hi v[0:1], v2, off
	v_mul_f32_e32 v2, 0x3ab504f3, v5
	v_bfe_u32 v3, v2, 16, 1
	v_accvgpr_read_b32 v6, a14
	v_add3_u32 v2, v2, v3, s80
	global_store_short_d16_hi v[0:1], v2, off offset:512
	v_mul_f32_e32 v2, 0x3ab504f3, v6
	v_bfe_u32 v3, v2, 16, 1
	v_add_co_u32_e32 v0, vcc, 0x20000, v0
	v_accvgpr_read_b32 v7, a15
	v_add3_u32 v2, v2, v3, s80
	v_addc_co_u32_e32 v1, vcc, 0, v1, vcc
	global_store_short_d16_hi v[0:1], v2, off
	v_mul_f32_e32 v2, 0x3ab504f3, v7
	v_bfe_u32 v3, v2, 16, 1
	v_add3_u32 v2, v2, v3, s80
	global_store_short_d16_hi v[0:1], v2, off offset:512
	s_cbranch_execnz .LBB0_249

.LBB0_374:
	s_andn2_b64 vcc, exec, s[0:1]
	s_cbranch_vccnz .LBB0_376
	s_add_i32 s5, s97, 0xfffffbe0
	s_lshr_b32 s78, s5, 8
	s_lshl_b64 s[0:1], s[78:79], 23
	v_readlane_b32 s2, v254, 5
	s_add_u32 s0, s2, s0
	v_readlane_b32 s2, v254, 6
	s_addc_u32 s1, s2, s1
	s_lshl_b64 s[2:3], s[78:79], 22
	v_readlane_b32 s4, v254, 11
	s_waitcnt vmcnt(7)
	v_mov_b32_e32 v37, v208
	s_add_u32 s2, s4, s2
	v_readlane_b32 s4, v254, 12
	s_addc_u32 s3, s4, s3
	v_lshlrev_b32_e32 v1, 7, v37
	s_lshl_b32 s4, s97, 7
	v_lshrrev_b32_e32 v0, 5, v37
	v_and_b32_e32 v5, 7, v37
	v_and_b32_e32 v39, 0x2f80, v1
	v_ashrrev_i32_e32 v1, 1, v37
	s_and_b32 s4, s4, 0x80
	v_and_b32_e32 v36, 31, v37
	v_and_b32_e32 v38, 0xffffffc0, v1
	v_bitop3_b32 v0, v0, v5, 1 bitop3:0x6c
	v_ashrrev_i32_e32 v110, 3, v37
	v_or_b32_e32 v1, v38, v36
	v_lshlrev_b32_e32 v109, 4, v0
	v_add_u32_e32 v0, s4, v110
	v_lshl_add_u32 v108, v1, 7, v214
	v_ashrrev_i32_e32 v1, 31, v0
	v_readlane_b32 s6, v253, 40
	v_lshlrev_b64 v[0:1], 8, v[0:1]
	v_readlane_b32 s7, v253, 41
	v_lshlrev_b32_e32 v3, 4, v37
	v_and_b32_e32 v192, 0x70, v3
	v_lshl_add_u64 v[0:1], s[6:7], 0, v[0:1]
	v_lshl_add_u64 v[32:33], v[0:1], 0, v[192:193]
	global_load_dwordx4 v[40:43], v[32:33], off
	v_ashrrev_i32_e32 v86, 4, v37
	s_lshl_b32 s5, s5, 6
	v_ashrrev_i32_e32 v87, 31, v86
	s_and_b32 s5, s5, 0x3f80
	v_lshlrev_b32_e32 v2, 3, v37
	v_lshlrev_b64 v[0:1], 15, v[86:87]
	v_lshl_add_u64 v[0:1], s[2:3], 0, v[0:1]
	s_lshl_b32 s78, s5, 1
	v_and_b32_e32 v87, 0x78, v2
	v_add_u32_e32 v7, 0x100, v37
	v_lshl_add_u64 v[0:1], v[0:1], 0, s[78:79]
	v_lshlrev_b32_e32 v2, 1, v87
	v_mov_b32_e32 v3, v193
	v_ashrrev_i32_e32 v111, 3, v7
	v_lshl_add_u64 v[12:13], v[0:1], 0, v[2:3]
	v_add_u32_e32 v0, s4, v111
	v_ashrrev_i32_e32 v1, 31, v0
	v_lshlrev_b64 v[0:1], 8, v[0:1]
	v_bfe_u32 v4, v37, 5, 1
	v_lshl_add_u64 v[0:1], s[6:7], 0, v[0:1]
	v_lshl_add_u64 v[34:35], v[0:1], 0, v[192:193]
	v_bitop3_b32 v0, v4, v5, 4 bitop3:0x36
	v_ashrrev_i32_e32 v88, 4, v7
	v_lshlrev_b32_e32 v113, 4, v0
	v_bitop3_b32 v0, v4, v5, 6 bitop3:0x36
	v_ashrrev_i32_e32 v89, 31, v88
	v_lshlrev_b32_e32 v114, 4, v0
	v_lshlrev_b64 v[0:1], 15, v[88:89]
	v_bitop3_b32 v6, v4, v5, 2 bitop3:0x36
	v_lshl_add_u64 v[0:1], s[2:3], 0, v[0:1]
	v_add_u32_e32 v4, 0x200, v37
	v_lshl_add_u64 v[0:1], v[0:1], 0, s[78:79]
	v_ashrrev_i32_e32 v89, 3, v4
	v_lshl_add_u64 v[14:15], v[0:1], 0, v[2:3]
	v_add_u32_e32 v0, s4, v89
	v_ashrrev_i32_e32 v1, 31, v0
	v_lshlrev_b64 v[0:1], 8, v[0:1]
	v_ashrrev_i32_e32 v94, 4, v4
	v_lshl_add_u64 v[0:1], s[6:7], 0, v[0:1]
	v_ashrrev_i32_e32 v95, 31, v94
	v_lshl_add_u64 v[90:91], v[0:1], 0, v[192:193]
	v_lshlrev_b64 v[0:1], 15, v[94:95]
	v_lshl_add_u64 v[0:1], s[2:3], 0, v[0:1]
	v_add_u32_e32 v8, 0x300, v37
	v_lshl_add_u64 v[0:1], v[0:1], 0, s[78:79]
	v_ashrrev_i32_e32 v95, 3, v8
	v_lshl_add_u64 v[24:25], v[0:1], 0, v[2:3]
	v_add_u32_e32 v0, s4, v95
	v_ashrrev_i32_e32 v1, 31, v0
	v_lshlrev_b64 v[0:1], 8, v[0:1]
	v_ashrrev_i32_e32 v98, 4, v8
	v_lshl_add_u64 v[0:1], s[6:7], 0, v[0:1]
	v_ashrrev_i32_e32 v99, 31, v98
	v_lshl_add_u64 v[96:97], v[0:1], 0, v[192:193]
	v_lshlrev_b64 v[0:1], 15, v[98:99]
	v_lshl_add_u64 v[0:1], s[2:3], 0, v[0:1]
	v_lshl_add_u64 v[0:1], v[0:1], 0, s[78:79]
	v_lshl_add_u64 v[26:27], v[0:1], 0, v[2:3]
	v_xor_b32_e32 v0, v110, v37
	v_lshlrev_b32_e32 v0, 4, v0
	v_and_b32_e32 v0, 0x70, v0
	global_load_dwordx4 v[44:47], v[34:35], off
	global_load_dwordx4 v[48:51], v[12:13], off
	v_lshlrev_b32_e32 v112, 4, v6
	global_load_dwordx4 v[4:7], v[34:35], off offset:128
	global_load_dwordx4 v[52:55], v[14:15], off
	global_load_dwordx4 v[16:19], v[32:33], off offset:128
	global_load_dwordx4 v[56:59], v[90:91], off
	global_load_dwordx4 v[8:11], v[90:91], off offset:128
	s_waitcnt vmcnt(12)
	v_lshl_or_b32 v152, v110, 7, v0
	v_bfe_u32 v231, v208, 6, 2
	v_lshlrev_b32_e32 v231, 4, v231
	v_xor_b32_e32 v152, v231, v152
	global_load_dwordx4 v[60:63], v[96:97], off
	global_load_dwordx4 v[64:67], v[24:25], off
	global_load_dwordx4 v[0:3], v[96:97], off offset:128
	global_load_dwordx4 v[82:85], v[26:27], off
	s_mov_b32 s2, 0x200000
	v_add_co_u32_e32 v100, vcc, s2, v12
	s_movk_i32 s3, 0x50
	s_nop 0
	v_addc_co_u32_e32 v101, vcc, 0, v13, vcc
	v_add_co_u32_e32 v102, vcc, s2, v14
	s_movk_i32 s6, 0x60
	s_nop 0
	v_addc_co_u32_e32 v103, vcc, 0, v15, vcc
	v_add_co_u32_e32 v104, vcc, s2, v24
	global_load_dwordx4 v[28:31], v[100:101], off
	global_load_dwordx4 v[20:23], v[102:103], off
	v_addc_co_u32_e32 v105, vcc, 0, v25, vcc
	v_add_co_u32_e32 v106, vcc, s2, v26
	s_movk_i32 s2, 0x70
	s_nop 0
	v_addc_co_u32_e32 v107, vcc, 0, v27, vcc
	global_load_dwordx4 v[24:27], v[104:105], off
	global_load_dwordx4 v[12:15], v[106:107], off
	s_waitcnt vmcnt(15)
	ds_write_b128 v152, v[40:43]
	v_lshlrev_b32_e32 v40, 1, v86
	v_lshlrev_b32_e32 v41, 7, v87
	v_and_b32_e32 v42, -16, v110
	v_and_b32_e32 v40, 14, v40
	v_add_u32_e32 v43, v41, v42
	v_or_b32_e32 v153, v43, v40
	v_xad_u32 v43, v42, 16, v41
	v_or_b32_e32 v154, v43, v40
	v_xad_u32 v43, v42, 32, v41
	v_or_b32_e32 v155, v43, v40
	v_xad_u32 v43, v42, 48, v41
	v_or_b32_e32 v156, v43, v40
	v_xad_u32 v43, v42, 64, v41
	v_or_b32_e32 v157, v43, v40
	v_xad_u32 v43, v42, s3, v41
	v_or_b32_e32 v158, v43, v40
	v_xad_u32 v43, v42, s6, v41
	v_xad_u32 v42, v42, s2, v41
	v_or_b32_e32 v159, v43, v40
	v_or_b32_e32 v160, v42, v40
	v_xor_b32_e32 v40, v111, v37
	v_lshlrev_b32_e32 v40, 4, v40
	v_and_b32_e32 v40, 0x70, v40
	v_lshl_or_b32 v164, v111, 7, v40
	v_bfe_u32 v231, v208, 6, 2
	v_lshlrev_b32_e32 v231, 4, v231
	v_xor_b32_e32 v164, v231, v164
	v_lshlrev_b32_e32 v40, 1, v88
	v_and_b32_e32 v42, -16, v111
	v_and_b32_e32 v40, 14, v40
	v_add_u32_e32 v43, v41, v42
	v_or_b32_e32 v165, v43, v40
	v_xad_u32 v43, v42, 16, v41
	v_or_b32_e32 v166, v43, v40
	v_xad_u32 v43, v42, 32, v41
	v_or_b32_e32 v167, v43, v40
	v_xad_u32 v43, v42, 48, v41
	v_or_b32_e32 v168, v43, v40
	v_xad_u32 v43, v42, 64, v41
	v_or_b32_e32 v169, v43, v40
	v_xad_u32 v43, v42, s3, v41
	v_or_b32_e32 v170, v43, v40
	v_xad_u32 v43, v42, s6, v41
	v_xad_u32 v42, v42, s2, v41
	v_or_b32_e32 v171, v43, v40
	v_or_b32_e32 v172, v42, v40
	v_xor_b32_e32 v40, v89, v37
	v_lshlrev_b32_e32 v40, 4, v40
	v_and_b32_e32 v40, 0x70, v40
	v_lshl_or_b32 v174, v89, 7, v40
	v_bfe_u32 v231, v208, 6, 2
	v_lshlrev_b32_e32 v231, 4, v231
	v_xor_b32_e32 v174, v231, v174
	v_lshlrev_b32_e32 v40, 1, v94
	v_and_b32_e32 v42, -16, v89
	v_and_b32_e32 v40, 14, v40
	v_add_u32_e32 v43, v41, v42
	v_or_b32_e32 v175, v43, v40
	v_xad_u32 v43, v42, 16, v41
	v_or_b32_e32 v176, v43, v40
	v_xad_u32 v43, v42, 32, v41
	v_or_b32_e32 v177, v43, v40
	v_xad_u32 v43, v42, 48, v41
	v_or_b32_e32 v178, v43, v40
	v_xad_u32 v43, v42, 64, v41
	v_or_b32_e32 v179, v43, v40
	v_xad_u32 v43, v42, s3, v41
	v_or_b32_e32 v180, v43, v40
	v_xad_u32 v43, v42, s6, v41
	v_xad_u32 v42, v42, s2, v41
	v_or_b32_e32 v181, v43, v40
	v_or_b32_e32 v182, v42, v40
	v_xor_b32_e32 v40, v95, v37
	v_lshlrev_b32_e32 v40, 4, v40
	v_and_b32_e32 v40, 0x70, v40
	v_lshl_or_b32 v183, v95, 7, v40
	v_bfe_u32 v231, v208, 6, 2
	v_lshlrev_b32_e32 v231, 4, v231
	v_xor_b32_e32 v183, v231, v183
	v_lshlrev_b32_e32 v40, 1, v98
	v_and_b32_e32 v42, -16, v95
	v_and_b32_e32 v40, 14, v40
	v_add_u32_e32 v43, v41, v42
	v_or_b32_e32 v184, v43, v40
	v_xad_u32 v43, v42, 16, v41
	v_or_b32_e32 v185, v43, v40
	v_xad_u32 v43, v42, 32, v41
	v_or_b32_e32 v186, v43, v40
	v_xad_u32 v43, v42, 48, v41
	v_or_b32_e32 v187, v43, v40
	v_xad_u32 v43, v42, 64, v41
	v_or_b32_e32 v188, v43, v40
	v_xad_u32 v43, v42, s3, v41
	v_or_b32_e32 v189, v43, v40
	v_xad_u32 v43, v42, s6, v41
	v_xad_u32 v41, v42, s2, v41
	v_or_b32_e32 v190, v43, v40
	v_or_b32_e32 v191, v41, v40
	v_and_b32_e32 v75, 7, v208
	v_lshlrev_b32_e32 v75, 4, v75
	v_bfe_u32 v92, v208, 3, 2
	v_lshlrev_b32_e32 v92, 4, v92
	v_xor_b32_e32 v153, v75, v153
	v_xor_b32_e32 v154, v75, v154
	v_xor_b32_e32 v155, v75, v155
	v_xor_b32_e32 v156, v75, v156
	v_xor_b32_e32 v157, v75, v157
	v_xor_b32_e32 v158, v75, v158
	v_xor_b32_e32 v159, v75, v159
	v_xor_b32_e32 v160, v75, v160
	v_xor_b32_e32 v165, v75, v165
	v_xor_b32_e32 v166, v75, v166
	v_xor_b32_e32 v167, v75, v167
	v_xor_b32_e32 v168, v75, v168
	v_xor_b32_e32 v169, v75, v169
	v_xor_b32_e32 v170, v75, v170
	v_xor_b32_e32 v171, v75, v171
	v_xor_b32_e32 v172, v75, v172
	v_xor_b32_e32 v175, v75, v175
	v_xor_b32_e32 v176, v75, v176
	v_xor_b32_e32 v177, v75, v177
	v_xor_b32_e32 v178, v75, v178
	v_xor_b32_e32 v179, v75, v179
	v_xor_b32_e32 v180, v75, v180
	v_xor_b32_e32 v181, v75, v181
	v_xor_b32_e32 v182, v75, v182
	v_xor_b32_e32 v184, v75, v184
	v_xor_b32_e32 v185, v75, v185
	v_xor_b32_e32 v186, v75, v186
	v_xor_b32_e32 v187, v75, v187
	v_xor_b32_e32 v188, v75, v188
	v_xor_b32_e32 v189, v75, v189
	v_xor_b32_e32 v190, v75, v190
	v_xor_b32_e32 v191, v75, v191
	s_waitcnt vmcnt(13)
	ds_write_b16 v153, v48 offset:16384
	ds_write_b16_d16_hi v154, v48 offset:16512
	ds_write_b16 v155, v49 offset:16640
	ds_write_b16_d16_hi v156, v49 offset:16768
	ds_write_b16 v157, v50 offset:16896
	ds_write_b16_d16_hi v158, v50 offset:17024
	ds_write_b16 v159, v51 offset:17152
	ds_write_b16_d16_hi v160, v51 offset:17280
	ds_write_b128 v164, v[44:47]
	s_waitcnt vmcnt(11)
	ds_write_b16 v165, v52 offset:16384
	ds_write_b16_d16_hi v166, v52 offset:16512
	ds_write_b16 v167, v53 offset:16640
	ds_write_b16_d16_hi v168, v53 offset:16768
	ds_write_b16 v169, v54 offset:16896
	ds_write_b16_d16_hi v170, v54 offset:17024
	ds_write_b16 v171, v55 offset:17152
	ds_write_b16_d16_hi v172, v55 offset:17280
	s_waitcnt vmcnt(9)
	ds_write_b128 v174, v[56:59]
	s_waitcnt vmcnt(6)
	ds_write_b16 v175, v64 offset:16384
	ds_write_b16_d16_hi v176, v64 offset:16512
	ds_write_b16 v177, v65 offset:16640
	ds_write_b16_d16_hi v178, v65 offset:16768
	ds_write_b16 v179, v66 offset:16896
	ds_write_b16_d16_hi v180, v66 offset:17024
	ds_write_b16 v181, v67 offset:17152
	ds_write_b16_d16_hi v182, v67 offset:17280
	ds_write_b128 v183, v[60:63]
	s_waitcnt vmcnt(4)
	ds_write_b16 v184, v82 offset:16384
	ds_write_b16_d16_hi v185, v82 offset:16512
	ds_write_b16 v186, v83 offset:16640
	ds_write_b16_d16_hi v187, v83 offset:16768
	ds_write_b16 v188, v84 offset:16896
	ds_write_b16_d16_hi v189, v84 offset:17024
	ds_write_b16 v190, v85 offset:17152
	ds_write_b16_d16_hi v191, v85 offset:17280
	s_waitcnt lgkmcnt(0)
	s_barrier

	s_nop 0

	s_nop 0


	v_or_b32_e32 v150, v108, v109
	v_xor_b32_e32 v150, v92, v150
	v_xor_b32_e32 v207, 64, v150
	v_or_b32_e32 v161, v109, v39
	v_bfe_u32 v231, v208, 3, 2
	v_lshlrev_b32_e32 v231, 4, v231
	v_xor_b32_e32 v161, v231, v161
	ds_read_b128 v[82:85], v161 offset:0
	ds_read_b128 v[86:89], v161 offset:0x1000
	ds_read_b128 v[94:97], v150 offset:0
	ds_read_b128 v[98:101], v207 offset:0x1000
	v_or_b32_e32 v151, v108, v113
	v_xor_b32_e32 v151, v92, v151
	v_xor_b32_e32 v221, 64, v151
	v_or_b32_e32 v162, v113, v39
	v_bfe_u32 v231, v208, 3, 2
	v_lshlrev_b32_e32 v231, 4, v231
	v_xor_b32_e32 v162, v231, v162
	v_or_b32_e32 v163, v108, v112
	v_xor_b32_e32 v163, v92, v163
	v_xor_b32_e32 v224, 64, v163
	v_or_b32_e32 v173, v114, v39
	v_bfe_u32 v231, v208, 3, 2
	v_lshlrev_b32_e32 v231, 4, v231
	v_xor_b32_e32 v173, v231, v173
	v_or_b32_e32 v39, v112, v39
	v_bfe_u32 v231, v208, 3, 2
	v_lshlrev_b32_e32 v231, 4, v231
	v_xor_b32_e32 v39, v231, v39
	v_or_b32_e32 v192, v108, v114
	v_xor_b32_e32 v192, v92, v192
	v_xor_b32_e32 v225, 64, v192
	ds_read_b128 v[102:105], v39 offset:0
	ds_read_b128 v[106:109], v39 offset:0x1000
	ds_read_b128 v[110:113], v163 offset:0
	ds_read_b128 v[114:117], v224 offset:0x1000
	ds_read_b128 v[118:121], v162 offset:0
	ds_read_b128 v[122:125], v162 offset:0x1000
	ds_read_b128 v[126:129], v151 offset:0
	ds_read_b128 v[130:133], v221 offset:0x1000
	ds_read_b128 v[134:137], v173 offset:0
	ds_read_b128 v[138:141], v173 offset:0x1000
	ds_read_b128 v[142:145], v192 offset:0
	ds_read_b128 v[146:149], v225 offset:0x1000
	s_waitcnt lgkmcnt(12)
	s_nop 0
	v_mfma_f32_32x32x16_bf16 a[48:63], v[82:85], v[94:97], 0
	s_waitcnt lgkmcnt(8)
	s_waitcnt lgkmcnt(4)
	s_waitcnt lgkmcnt(0)
	ds_write_b128 v152, v[16:19] offset:32768
	s_waitcnt vmcnt(3)
	ds_write_b16 v153, v28 offset:49152
	ds_write_b16_d16_hi v154, v28 offset:49280
	ds_write_b16 v155, v29 offset:49408
	ds_write_b16_d16_hi v156, v29 offset:49536
	ds_write_b16 v157, v30 offset:49664
	ds_write_b16_d16_hi v158, v30 offset:49792
	ds_write_b16 v159, v31 offset:49920
	ds_write_b16_d16_hi v160, v31 offset:50048
	ds_write_b128 v164, v[4:7] offset:32768
	s_waitcnt vmcnt(2)
	ds_write_b16 v165, v20 offset:49152
	ds_write_b16_d16_hi v166, v20 offset:49280
	ds_write_b16 v167, v21 offset:49408
	ds_write_b16_d16_hi v168, v21 offset:49536
	ds_write_b16 v169, v22 offset:49664
	ds_write_b16_d16_hi v170, v22 offset:49792
	ds_write_b16 v171, v23 offset:49920
	ds_write_b16_d16_hi v172, v23 offset:50048
	ds_write_b128 v174, v[8:11] offset:32768
	s_waitcnt vmcnt(1)
	ds_write_b16 v175, v24 offset:49152
	ds_write_b16_d16_hi v176, v24 offset:49280
	ds_write_b16 v177, v25 offset:49408
	ds_write_b16_d16_hi v178, v25 offset:49536
	ds_write_b16 v179, v26 offset:49664
	ds_write_b16_d16_hi v180, v26 offset:49792
	ds_write_b16 v181, v27 offset:49920
	ds_write_b16_d16_hi v182, v27 offset:50048
	ds_write_b128 v183, v[0:3] offset:32768
	s_waitcnt vmcnt(0)
	ds_write_b16 v184, v12 offset:49152
	ds_write_b16_d16_hi v185, v12 offset:49280
	ds_write_b16 v186, v13 offset:49408
	ds_write_b16_d16_hi v187, v13 offset:49536
	ds_write_b16 v188, v14 offset:49664
	ds_write_b16_d16_hi v189, v14 offset:49792
	ds_write_b16 v190, v15 offset:49920
	ds_write_b16_d16_hi v191, v15 offset:50048
	s_waitcnt lgkmcnt(0)
	s_barrier
	v_mfma_f32_32x32x16_bf16 a[48:63], v[102:105], v[110:113], a[48:63]
	ds_read_b128 v[0:3], v161 offset:0x8000
	ds_read_b128 v[4:7], v161 offset:0x9000
	ds_read_b128 v[8:11], v150 offset:0x8000
	ds_read_b128 v[12:15], v207 offset:0x9000
	ds_read_b128 v[16:19], v39 offset:0x8000
	ds_read_b128 v[20:23], v39 offset:0x9000
	ds_read_b128 v[24:27], v163 offset:0x8000
	v_mfma_f32_32x32x16_bf16 a[48:63], v[118:121], v[126:129], a[48:63]
	ds_read_b128 v[28:31], v224 offset:0x9000
	v_mfma_f32_32x32x16_bf16 a[32:47], v[82:85], v[98:101], 0
	ds_read_b128 v[82:85], v162 offset:0x8000
	v_mfma_f32_32x32x16_bf16 a[16:31], v[86:89], v[94:97], 0
	v_mfma_f32_32x32x16_bf16 a[0:15], v[86:89], v[98:101], 0
	ds_read_b128 v[86:89], v162 offset:0x9000
	ds_read_b128 v[94:97], v151 offset:0x8000
	ds_read_b128 v[98:101], v221 offset:0x9000
	v_mfma_f32_32x32x16_bf16 a[48:63], v[134:137], v[142:145], a[48:63]
	v_mfma_f32_32x32x16_bf16 a[32:47], v[102:105], v[114:117], a[32:47]
	ds_read_b128 v[102:105], v173 offset:0x8000
	v_mfma_f32_32x32x16_bf16 a[16:31], v[106:109], v[110:113], a[16:31]
	v_mfma_f32_32x32x16_bf16 a[0:15], v[106:109], v[114:117], a[0:15]
	ds_read_b128 v[106:109], v173 offset:0x9000
	ds_read_b128 v[110:113], v192 offset:0x8000
	ds_read_b128 v[114:117], v225 offset:0x9000
	s_waitcnt lgkmcnt(12)
	s_waitcnt lgkmcnt(8)
	s_waitcnt lgkmcnt(4)
	s_nop 0
	v_mfma_f32_32x32x16_bf16 a[48:63], v[0:3], v[8:11], a[48:63]
	s_waitcnt lgkmcnt(0)


	v_mfma_f32_32x32x16_bf16 a[32:47], v[118:121], v[130:133], a[32:47]
	v_mfma_f32_32x32x16_bf16 a[48:63], v[16:19], v[24:27], a[48:63]
	v_mfma_f32_32x32x16_bf16 a[16:31], v[122:125], v[126:129], a[16:31]
	v_mfma_f32_32x32x16_bf16 a[0:15], v[122:125], v[130:133], a[0:15]
	v_mfma_f32_32x32x16_bf16 a[32:47], v[134:137], v[146:149], a[32:47]
	v_mfma_f32_32x32x16_bf16 a[48:63], v[82:85], v[94:97], a[48:63]
	v_mfma_f32_32x32x16_bf16 a[16:31], v[138:141], v[142:145], a[16:31]
	v_mfma_f32_32x32x16_bf16 a[0:15], v[138:141], v[146:149], a[0:15]
	v_mfma_f32_32x32x16_bf16 a[32:47], v[0:3], v[12:15], a[32:47]
	v_lshrrev_b32_e32 v1, 3, v37
	v_and_b32_e32 v0, 64, v37
	v_and_b32_e32 v1, 4, v1
	v_or3_b32 v2, v0, v1, s4
	v_or_b32_e32 v0, s5, v36
	v_add_u32_e32 v0, v0, v38
	v_and_b32_e32 v1, 0xdf, v0
	v_mfma_f32_32x32x16_bf16 a[48:63], v[102:105], v[110:113], a[48:63]
	v_ashrrev_i32_e32 v0, 7, v0
	v_and_b32_e32 v3, -2, v0
	v_lshl_add_u32 v2, v2, 6, v3
	v_ashrrev_i32_e32 v3, 31, v2
	v_lshlrev_b32_e32 v192, 1, v1
	v_lshl_add_u64 v[0:1], s[0:1], 0, v[192:193]
	s_mov_b32 s0, 0x10000
	v_mfma_f32_32x32x16_bf16 a[16:31], v[4:7], v[8:11], a[16:31]
	v_mfma_f32_32x32x16_bf16 a[0:15], v[4:7], v[12:15], a[0:15]
	v_lshlrev_b64 v[4:5], 9, v[2:3]
	s_nop 1
	v_accvgpr_read_b32 v3, a48
	v_bfe_u32 v6, v3, 16, 1
	v_lshl_add_u64 v[4:5], v[0:1], 0, v[4:5]
	v_add3_u32 v3, v3, v6, s80
	global_store_short_d16_hi v[4:5], v3, off
	v_accvgpr_read_b32 v3, a49
	v_bfe_u32 v6, v3, 16, 1
	v_add3_u32 v3, v3, v6, s80
	global_store_short_d16_hi v[4:5], v3, off offset:512
	v_accvgpr_read_b32 v3, a50
	v_bfe_u32 v6, v3, 16, 1
	v_add3_u32 v3, v3, v6, s80
	v_add_co_u32_e32 v6, vcc, s0, v4
	v_mfma_f32_32x32x16_bf16 a[32:47], v[16:19], v[28:31], a[32:47]
	s_nop 0
	v_addc_co_u32_e32 v7, vcc, 0, v5, vcc
	global_store_short_d16_hi v[6:7], v3, off
	v_accvgpr_read_b32 v3, a51
	v_bfe_u32 v8, v3, 16, 1
	v_add3_u32 v3, v3, v8, s80
	v_add_u32_e32 v8, 0x200, v2
	global_store_short_d16_hi v[6:7], v3, off offset:512
	v_ashrrev_i32_e32 v9, 31, v8
	v_accvgpr_read_b32 v3, a52
	v_lshlrev_b64 v[8:9], 9, v[8:9]
	v_bfe_u32 v10, v3, 16, 1
	v_lshl_add_u64 v[8:9], v[0:1], 0, v[8:9]
	v_add3_u32 v3, v3, v10, s80
	global_store_short_d16_hi v[8:9], v3, off
	v_accvgpr_read_b32 v3, a53
	v_bfe_u32 v10, v3, 16, 1
	v_add3_u32 v3, v3, v10, s80
	global_store_short_d16_hi v[8:9], v3, off offset:512
	v_accvgpr_read_b32 v3, a54
	v_bfe_u32 v10, v3, 16, 1
	v_add3_u32 v3, v3, v10, s80
	v_add_co_u32_e32 v10, vcc, s0, v8
	v_mfma_f32_32x32x16_bf16 a[32:47], v[82:85], v[98:101], a[32:47]
	s_nop 0
	v_addc_co_u32_e32 v11, vcc, 0, v9, vcc
	global_store_short_d16_hi v[10:11], v3, off
	v_accvgpr_read_b32 v3, a55
	v_bfe_u32 v12, v3, 16, 1
	v_add3_u32 v3, v3, v12, s80
	v_add_u32_e32 v12, 0x400, v2
	global_store_short_d16_hi v[10:11], v3, off offset:512
	v_ashrrev_i32_e32 v13, 31, v12
	v_accvgpr_read_b32 v3, a56
	v_lshlrev_b64 v[12:13], 9, v[12:13]
	v_bfe_u32 v14, v3, 16, 1
	v_lshl_add_u64 v[12:13], v[0:1], 0, v[12:13]
	v_add3_u32 v3, v3, v14, s80
	global_store_short_d16_hi v[12:13], v3, off
	v_accvgpr_read_b32 v3, a57
	v_bfe_u32 v14, v3, 16, 1
	v_add3_u32 v3, v3, v14, s80
	global_store_short_d16_hi v[12:13], v3, off offset:512
	v_accvgpr_read_b32 v3, a58
	v_bfe_u32 v14, v3, 16, 1
	v_add3_u32 v3, v3, v14, s80
	v_add_co_u32_e32 v14, vcc, s0, v12
	v_mfma_f32_32x32x16_bf16 a[32:47], v[102:105], v[114:117], a[32:47]
	s_nop 0
	v_addc_co_u32_e32 v15, vcc, 0, v13, vcc
	global_store_short_d16_hi v[14:15], v3, off
	v_accvgpr_read_b32 v3, a59
	v_bfe_u32 v16, v3, 16, 1
	v_add3_u32 v3, v3, v16, s80
	v_add_u32_e32 v16, 0x600, v2
	global_store_short_d16_hi v[14:15], v3, off offset:512
	v_ashrrev_i32_e32 v17, 31, v16
	v_accvgpr_read_b32 v3, a60
	v_lshlrev_b64 v[16:17], 9, v[16:17]
	v_bfe_u32 v18, v3, 16, 1
	v_lshl_add_u64 v[16:17], v[0:1], 0, v[16:17]
	v_add3_u32 v3, v3, v18, s80
	global_store_short_d16_hi v[16:17], v3, off
	v_accvgpr_read_b32 v3, a61
	v_bfe_u32 v18, v3, 16, 1
	v_add3_u32 v3, v3, v18, s80
	global_store_short_d16_hi v[16:17], v3, off offset:512
	v_accvgpr_read_b32 v3, a62
	v_bfe_u32 v18, v3, 16, 1
	v_add3_u32 v3, v3, v18, s80
	v_add_co_u32_e32 v18, vcc, s0, v16
	v_mfma_f32_32x32x16_bf16 a[16:31], v[20:23], v[24:27], a[16:31]
	s_nop 0
	v_addc_co_u32_e32 v19, vcc, 0, v17, vcc
	global_store_short_d16_hi v[18:19], v3, off
	v_accvgpr_read_b32 v3, a63
	v_mfma_f32_32x32x16_bf16 a[0:15], v[20:23], v[28:31], a[0:15]
	v_bfe_u32 v20, v3, 16, 1
	v_add3_u32 v3, v3, v20, s80
	global_store_short_d16_hi v[18:19], v3, off offset:512
	v_accvgpr_read_b32 v3, a32
	v_bfe_u32 v20, v3, 16, 1
	v_add3_u32 v3, v3, v20, s80
	global_store_short_d16_hi v[4:5], v3, off offset:64
	v_accvgpr_read_b32 v3, a33
	v_bfe_u32 v20, v3, 16, 1
	v_add3_u32 v3, v3, v20, s80
	global_store_short_d16_hi v[4:5], v3, off offset:576
	v_accvgpr_read_b32 v3, a34
	v_bfe_u32 v4, v3, 16, 1
	v_add3_u32 v3, v3, v4, s80
	global_store_short_d16_hi v[6:7], v3, off offset:64
	v_accvgpr_read_b32 v3, a35
	v_bfe_u32 v4, v3, 16, 1
	v_add3_u32 v3, v3, v4, s80
	global_store_short_d16_hi v[6:7], v3, off offset:576
	v_accvgpr_read_b32 v3, a36
	v_bfe_u32 v4, v3, 16, 1
	v_add3_u32 v3, v3, v4, s80
	global_store_short_d16_hi v[8:9], v3, off offset:64
	v_accvgpr_read_b32 v3, a37
	v_bfe_u32 v4, v3, 16, 1
	v_add3_u32 v3, v3, v4, s80
	global_store_short_d16_hi v[8:9], v3, off offset:576
	v_accvgpr_read_b32 v3, a38
	v_bfe_u32 v4, v3, 16, 1
	v_add3_u32 v3, v3, v4, s80
	global_store_short_d16_hi v[10:11], v3, off offset:64
	v_accvgpr_read_b32 v3, a39
	v_bfe_u32 v4, v3, 16, 1
	v_add3_u32 v3, v3, v4, s80
	global_store_short_d16_hi v[10:11], v3, off offset:576
	v_accvgpr_read_b32 v3, a40
	v_bfe_u32 v4, v3, 16, 1
	v_add3_u32 v3, v3, v4, s80
	global_store_short_d16_hi v[12:13], v3, off offset:64
	v_accvgpr_read_b32 v3, a41
	v_bfe_u32 v4, v3, 16, 1
	v_add3_u32 v3, v3, v4, s80
	global_store_short_d16_hi v[12:13], v3, off offset:576
	v_accvgpr_read_b32 v3, a42
	v_bfe_u32 v4, v3, 16, 1
	v_mfma_f32_32x32x16_bf16 a[16:31], v[86:89], v[94:97], a[16:31]
	v_add3_u32 v3, v3, v4, s80
	global_store_short_d16_hi v[14:15], v3, off offset:64
	v_accvgpr_read_b32 v3, a43
	v_bfe_u32 v4, v3, 16, 1
	v_add3_u32 v3, v3, v4, s80
	global_store_short_d16_hi v[14:15], v3, off offset:576
	v_accvgpr_read_b32 v3, a44
	v_bfe_u32 v4, v3, 16, 1
	v_add3_u32 v3, v3, v4, s80
	global_store_short_d16_hi v[16:17], v3, off offset:64
	v_accvgpr_read_b32 v3, a45
	v_mfma_f32_32x32x16_bf16 a[16:31], v[106:109], v[110:113], a[16:31]
	v_bfe_u32 v4, v3, 16, 1
	v_add3_u32 v3, v3, v4, s80
	global_store_short_d16_hi v[16:17], v3, off offset:576
	v_accvgpr_read_b32 v3, a46
	v_bfe_u32 v4, v3, 16, 1
	v_add3_u32 v3, v3, v4, s80
	global_store_short_d16_hi v[18:19], v3, off offset:64
	v_accvgpr_read_b32 v3, a47
	v_bfe_u32 v4, v3, 16, 1
	v_add3_u32 v3, v3, v4, s80
	v_add_u32_e32 v4, 0x800, v2
	global_store_short_d16_hi v[18:19], v3, off offset:576
	v_ashrrev_i32_e32 v5, 31, v4
	v_accvgpr_read_b32 v3, a16
	v_lshlrev_b64 v[4:5], 9, v[4:5]
	v_bfe_u32 v6, v3, 16, 1
	v_lshl_add_u64 v[4:5], v[0:1], 0, v[4:5]
	v_add3_u32 v3, v3, v6, s80
	global_store_short_d16_hi v[4:5], v3, off
	v_accvgpr_read_b32 v3, a17
	v_bfe_u32 v6, v3, 16, 1
	v_add3_u32 v3, v3, v6, s80
	global_store_short_d16_hi v[4:5], v3, off offset:512
	v_accvgpr_read_b32 v3, a18
	v_bfe_u32 v6, v3, 16, 1
	v_add3_u32 v3, v3, v6, s80
	v_add_co_u32_e32 v6, vcc, s0, v4
	v_mfma_f32_32x32x16_bf16 a[0:15], v[86:89], v[98:101], a[0:15]
	s_nop 0
	v_addc_co_u32_e32 v7, vcc, 0, v5, vcc
	global_store_short_d16_hi v[6:7], v3, off
	v_accvgpr_read_b32 v3, a19
	v_bfe_u32 v8, v3, 16, 1
	v_add3_u32 v3, v3, v8, s80
	v_add_u32_e32 v8, 0xa00, v2
	global_store_short_d16_hi v[6:7], v3, off offset:512
	v_ashrrev_i32_e32 v9, 31, v8
	v_accvgpr_read_b32 v3, a20
	v_lshlrev_b64 v[8:9], 9, v[8:9]
	v_bfe_u32 v10, v3, 16, 1
	v_lshl_add_u64 v[8:9], v[0:1], 0, v[8:9]
	v_add3_u32 v3, v3, v10, s80
	global_store_short_d16_hi v[8:9], v3, off
	v_accvgpr_read_b32 v3, a21
	v_bfe_u32 v10, v3, 16, 1
	v_add3_u32 v3, v3, v10, s80
	global_store_short_d16_hi v[8:9], v3, off offset:512
	v_accvgpr_read_b32 v3, a22
	v_bfe_u32 v10, v3, 16, 1
	v_add3_u32 v3, v3, v10, s80
	v_add_co_u32_e32 v10, vcc, s0, v8
	v_mfma_f32_32x32x16_bf16 a[0:15], v[106:109], v[114:117], a[0:15]
	s_nop 0
	v_addc_co_u32_e32 v11, vcc, 0, v9, vcc
	global_store_short_d16_hi v[10:11], v3, off
	v_accvgpr_read_b32 v3, a23
	v_bfe_u32 v12, v3, 16, 1
	v_add3_u32 v3, v3, v12, s80
	v_add_u32_e32 v12, 0xc00, v2
	global_store_short_d16_hi v[10:11], v3, off offset:512
	v_ashrrev_i32_e32 v13, 31, v12
	v_accvgpr_read_b32 v3, a24
	v_lshlrev_b64 v[12:13], 9, v[12:13]
	v_bfe_u32 v14, v3, 16, 1
	v_lshl_add_u64 v[12:13], v[0:1], 0, v[12:13]
	v_add3_u32 v3, v3, v14, s80
	global_store_short_d16_hi v[12:13], v3, off
	v_accvgpr_read_b32 v3, a25
	v_bfe_u32 v14, v3, 16, 1
	v_add3_u32 v3, v3, v14, s80
	global_store_short_d16_hi v[12:13], v3, off offset:512
	v_accvgpr_read_b32 v3, a26
	v_bfe_u32 v14, v3, 16, 1
	v_add3_u32 v3, v3, v14, s80
	v_add_co_u32_e32 v14, vcc, s0, v12
	v_add_u32_e32 v2, 0xe00, v2
	s_nop 0
	v_addc_co_u32_e32 v15, vcc, 0, v13, vcc
	global_store_short_d16_hi v[14:15], v3, off
	v_accvgpr_read_b32 v3, a27
	v_bfe_u32 v16, v3, 16, 1
	v_add3_u32 v3, v3, v16, s80
	global_store_short_d16_hi v[14:15], v3, off offset:512
	v_ashrrev_i32_e32 v3, 31, v2
	v_lshlrev_b64 v[2:3], 9, v[2:3]
	v_lshl_add_u64 v[0:1], v[0:1], 0, v[2:3]
	v_accvgpr_read_b32 v2, a28
	v_bfe_u32 v3, v2, 16, 1
	v_add3_u32 v2, v2, v3, s80
	global_store_short_d16_hi v[0:1], v2, off
	v_accvgpr_read_b32 v2, a29
	v_bfe_u32 v3, v2, 16, 1
	v_add3_u32 v2, v2, v3, s80
	global_store_short_d16_hi v[0:1], v2, off offset:512
	v_accvgpr_read_b32 v2, a30
	v_bfe_u32 v3, v2, 16, 1
	v_add3_u32 v16, v2, v3, s80
	v_add_co_u32_e32 v2, vcc, s0, v0
	s_nop 1
	v_addc_co_u32_e32 v3, vcc, 0, v1, vcc
	global_store_short_d16_hi v[2:3], v16, off
	v_accvgpr_read_b32 v16, a31
	v_bfe_u32 v17, v16, 16, 1
	v_add3_u32 v16, v16, v17, s80
	global_store_short_d16_hi v[2:3], v16, off offset:512
	v_accvgpr_read_b32 v16, a0
	v_bfe_u32 v17, v16, 16, 1
	v_add3_u32 v16, v16, v17, s80
	global_store_short_d16_hi v[4:5], v16, off offset:64
	v_accvgpr_read_b32 v16, a1
	v_bfe_u32 v17, v16, 16, 1
	v_add3_u32 v16, v16, v17, s80
	global_store_short_d16_hi v[4:5], v16, off offset:576
	v_accvgpr_read_b32 v4, a2
	v_bfe_u32 v5, v4, 16, 1
	v_add3_u32 v4, v4, v5, s80
	global_store_short_d16_hi v[6:7], v4, off offset:64
	v_accvgpr_read_b32 v4, a3
	v_bfe_u32 v5, v4, 16, 1
	v_add3_u32 v4, v4, v5, s80
	global_store_short_d16_hi v[6:7], v4, off offset:576
	v_accvgpr_read_b32 v4, a4
	v_bfe_u32 v5, v4, 16, 1
	v_add3_u32 v4, v4, v5, s80
	global_store_short_d16_hi v[8:9], v4, off offset:64
	v_accvgpr_read_b32 v4, a5
	v_bfe_u32 v5, v4, 16, 1
	v_add3_u32 v4, v4, v5, s80
	global_store_short_d16_hi v[8:9], v4, off offset:576
	v_accvgpr_read_b32 v4, a6
	v_bfe_u32 v5, v4, 16, 1
	v_add3_u32 v4, v4, v5, s80
	global_store_short_d16_hi v[10:11], v4, off offset:64
	v_accvgpr_read_b32 v4, a7
	v_bfe_u32 v5, v4, 16, 1
	v_add3_u32 v4, v4, v5, s80
	global_store_short_d16_hi v[10:11], v4, off offset:576
	v_accvgpr_read_b32 v4, a8
	v_bfe_u32 v5, v4, 16, 1
	v_add3_u32 v4, v4, v5, s80
	global_store_short_d16_hi v[12:13], v4, off offset:64
	v_accvgpr_read_b32 v4, a9
	v_bfe_u32 v5, v4, 16, 1
	v_add3_u32 v4, v4, v5, s80
	global_store_short_d16_hi v[12:13], v4, off offset:576
	v_accvgpr_read_b32 v4, a10
	v_bfe_u32 v5, v4, 16, 1
	v_add3_u32 v4, v4, v5, s80
	global_store_short_d16_hi v[14:15], v4, off offset:64
	v_accvgpr_read_b32 v4, a11
	v_bfe_u32 v5, v4, 16, 1
	v_add3_u32 v4, v4, v5, s80
	global_store_short_d16_hi v[14:15], v4, off offset:576
	v_accvgpr_read_b32 v4, a12
	v_bfe_u32 v5, v4, 16, 1
	v_add3_u32 v4, v4, v5, s80
	global_store_short_d16_hi v[0:1], v4, off offset:64
	v_accvgpr_read_b32 v4, a13
	v_bfe_u32 v5, v4, 16, 1
	v_add3_u32 v4, v4, v5, s80
	global_store_short_d16_hi v[0:1], v4, off offset:576
	v_accvgpr_read_b32 v0, a14
	v_bfe_u32 v1, v0, 16, 1
	v_add3_u32 v0, v0, v1, s80
	global_store_short_d16_hi v[2:3], v0, off offset:64
	v_accvgpr_read_b32 v0, a15
	v_bfe_u32 v1, v0, 16, 1
	v_add3_u32 v0, v0, v1, s80
	global_store_short_d16_hi v[2:3], v0, off offset:576
